# RG-LRU prefetch placement v2: x row piece i requested right after conv row i (running pointer), rows 8-10 and gate piece spread through the gate stage; on top of the S5 blocked scan
# speedup vs baseline: 1.0082x; 1.0017x over previous
; #define LAS __attribute__((address_space(3)))
; __device__ __forceinline__ unsigned cvt_pk_bf16(float lo, float hi) { unsigned r; asm("v_cvt_pk_bf16_f32 %0, %1, %2" : "=v"(r) : "v"(lo), "v"(hi)); return r; }
; __device__ __forceinline__ void lru_item(const Args& a, LAS unsigned char* lds, bool sample, int b, int head, int q, int tid, int lane, int wave) {
;     ...
;         for (int chk = 0; chk < 8; ++chk) {
;             const int R0 = b * SEQ + chk * 256, r0 = rg * 8;
; #pragma unroll
;             for (int rr = 0; rr < 8; ++rr) {
;                 const f32x4 xc = cb + cw0 * xin[rr] + cw1 * xin[rr + 1] + cw2 * xin[rr + 2] + cw3 * xin[rr + 3];
;                 u32x2 w; w.x = cvt_pk_bf16(xc[0], xc[1]); w.y = cvt_pk_bf16(xc[2], xc[3]);
;                 *(LAS u32x2*)(XC + (r0 + rr) * XC_PITCH + 8 * cq) = w;
;                 if ((cq >> 2) == q) *(LAS f32x4*)(XCF + (r0 + rr) * 16 + 4 * (cq & 3)) = xc;
;             }
;             const u32x4 gw = ggn;
;             if (chk < 7) {
;                 const float* p = XL + (size_t)(R0 + 256 + r0 - 3) * DH + cch;
; #pragma unroll
;                 for (int i = 0; i < 11; ++i) xin[i] = *(const f32x4*)(p + (size_t)i * DH);
;                 ggn = *(const u32x4*)(GG + (size_t)(R0 + 256 + er) * DH + ch0 + 8 * eh);
;             }
.LBB0_672:
	s_mov_b64 s[100:101], 0x1000
	v_add_u32_e32 v224, s30, v182
	v_ashrrev_i32_e32 v225, 31, v224
	v_lshlrev_b64 v[224:225], 12, v[224:225]
	v_lshl_add_u64 v[224:225], v[110:111], 0, v[224:225]
	v_pk_fma_f32 v[50:51], v[32:33], v[88:89], v[36:37]
	v_pk_fma_f32 v[52:53], v[30:31], v[86:87], v[34:35]
	v_pk_fma_f32 v[50:51], v[28:29], v[84:85], v[50:51]
	v_pk_fma_f32 v[52:53], v[26:27], v[82:83], v[52:53]
	v_pk_fma_f32 v[50:51], v[24:25], v[80:81], v[50:51]
	v_pk_fma_f32 v[86:87], v[22:23], v[78:79], v[52:53]
	v_pk_fma_f32 v[52:53], v[20:21], v[72:73], v[50:51]
	v_pk_fma_f32 v[50:51], v[18:19], v[70:71], v[86:87]
	v_cvt_pk_bf16_f32 v87, v52, v53
	s_nop 0
	v_cvt_pk_bf16_f32 v86, v50, v51
	ds_write_b64 v175, v[86:87]
	s_and_saveexec_b64 s[36:37], s[8:9]
	v_add_u32_e32 v86, v137, v138
	ds_write_b128 v86, v[50:53] offset:36864
	s_or_b64 exec, exec, s[36:37]
	global_load_dwordx4 v[86:89], v[224:225], off
	v_lshl_add_u64 v[224:225], v[224:225], 0, s[100:101]
	v_pk_fma_f32 v[50:51], v[32:33], v[84:85], v[36:37]
	v_pk_fma_f32 v[52:53], v[30:31], v[82:83], v[34:35]
	v_pk_fma_f32 v[50:51], v[28:29], v[80:81], v[50:51]
	v_pk_fma_f32 v[52:53], v[26:27], v[78:79], v[52:53]
	v_pk_fma_f32 v[50:51], v[24:25], v[72:73], v[50:51]
	v_pk_fma_f32 v[82:83], v[22:23], v[70:71], v[52:53]
	v_pk_fma_f32 v[52:53], v[20:21], v[68:69], v[50:51]
	v_pk_fma_f32 v[50:51], v[18:19], v[66:67], v[82:83]
	v_cvt_pk_bf16_f32 v83, v52, v53
	s_nop 0
	v_cvt_pk_bf16_f32 v82, v50, v51
	ds_write_b64 v176, v[82:83]
	s_and_saveexec_b64 s[36:37], s[8:9]
	v_add_u32_e32 v82, v137, v148
	ds_write_b128 v82, v[50:53] offset:36864
	s_or_b64 exec, exec, s[36:37]
	global_load_dwordx4 v[82:85], v[224:225], off
	v_lshl_add_u64 v[224:225], v[224:225], 0, s[100:101]
	v_pk_fma_f32 v[50:51], v[32:33], v[80:81], v[36:37]
	v_pk_fma_f32 v[52:53], v[30:31], v[78:79], v[34:35]
	v_pk_fma_f32 v[50:51], v[28:29], v[72:73], v[50:51]
	v_pk_fma_f32 v[52:53], v[26:27], v[70:71], v[52:53]
	v_pk_fma_f32 v[50:51], v[24:25], v[68:69], v[50:51]
	v_pk_fma_f32 v[78:79], v[22:23], v[66:67], v[52:53]
	v_pk_fma_f32 v[52:53], v[20:21], v[64:65], v[50:51]
	v_pk_fma_f32 v[50:51], v[18:19], v[62:63], v[78:79]
	v_cvt_pk_bf16_f32 v79, v52, v53
	s_nop 0
	v_cvt_pk_bf16_f32 v78, v50, v51
	ds_write_b64 v176, v[78:79] offset:144
	s_and_saveexec_b64 s[36:37], s[8:9]
	v_add_u32_e32 v78, v137, v149
	ds_write_b128 v78, v[50:53] offset:36864
	s_or_b64 exec, exec, s[36:37]
	global_load_dwordx4 v[78:81], v[224:225], off
	v_lshl_add_u64 v[224:225], v[224:225], 0, s[100:101]
	v_pk_fma_f32 v[50:51], v[32:33], v[72:73], v[36:37]
	v_pk_fma_f32 v[52:53], v[30:31], v[70:71], v[34:35]
	v_pk_fma_f32 v[50:51], v[28:29], v[68:69], v[50:51]
	v_pk_fma_f32 v[52:53], v[26:27], v[66:67], v[52:53]
	v_pk_fma_f32 v[50:51], v[24:25], v[64:65], v[50:51]
	v_pk_fma_f32 v[70:71], v[22:23], v[62:63], v[52:53]
	v_pk_fma_f32 v[52:53], v[20:21], v[60:61], v[50:51]
	v_pk_fma_f32 v[50:51], v[18:19], v[58:59], v[70:71]
	v_cvt_pk_bf16_f32 v71, v52, v53
	s_nop 0
	v_cvt_pk_bf16_f32 v70, v50, v51
	ds_write_b64 v176, v[70:71] offset:288
	s_and_saveexec_b64 s[36:37], s[8:9]
	v_add_u32_e32 v70, v137, v150
	ds_write_b128 v70, v[50:53] offset:36864
	s_or_b64 exec, exec, s[36:37]
	global_load_dwordx4 v[70:73], v[224:225], off
	v_lshl_add_u64 v[224:225], v[224:225], 0, s[100:101]
	v_pk_fma_f32 v[50:51], v[32:33], v[68:69], v[36:37]
	v_pk_fma_f32 v[52:53], v[30:31], v[66:67], v[34:35]
	v_pk_fma_f32 v[50:51], v[28:29], v[64:65], v[50:51]
	v_pk_fma_f32 v[52:53], v[26:27], v[62:63], v[52:53]
	v_pk_fma_f32 v[50:51], v[24:25], v[60:61], v[50:51]
	v_pk_fma_f32 v[66:67], v[22:23], v[58:59], v[52:53]
	v_pk_fma_f32 v[52:53], v[20:21], v[40:41], v[50:51]
	v_pk_fma_f32 v[50:51], v[18:19], v[38:39], v[66:67]
	v_cvt_pk_bf16_f32 v67, v52, v53
	s_nop 0
	v_cvt_pk_bf16_f32 v66, v50, v51
	ds_write_b64 v176, v[66:67] offset:432
	s_and_saveexec_b64 s[36:37], s[8:9]
	v_add_u32_e32 v66, v137, v151
	ds_write_b128 v66, v[50:53] offset:36864
	s_or_b64 exec, exec, s[36:37]
	global_load_dwordx4 v[66:69], v[224:225], off
	v_lshl_add_u64 v[224:225], v[224:225], 0, s[100:101]
	v_pk_fma_f32 v[50:51], v[32:33], v[64:65], v[36:37]
	v_pk_fma_f32 v[52:53], v[30:31], v[62:63], v[34:35]
	v_pk_fma_f32 v[50:51], v[28:29], v[60:61], v[50:51]
	v_pk_fma_f32 v[52:53], v[26:27], v[58:59], v[52:53]
	v_pk_fma_f32 v[50:51], v[24:25], v[40:41], v[50:51]
	v_pk_fma_f32 v[62:63], v[22:23], v[38:39], v[52:53]
	v_pk_fma_f32 v[52:53], v[20:21], v[48:49], v[50:51]
	v_pk_fma_f32 v[50:51], v[18:19], v[46:47], v[62:63]
	v_cvt_pk_bf16_f32 v63, v52, v53
	s_nop 0
	v_cvt_pk_bf16_f32 v62, v50, v51
	ds_write_b64 v176, v[62:63] offset:576
	s_and_saveexec_b64 s[36:37], s[8:9]
	v_add_u32_e32 v62, v137, v152
	ds_write_b128 v62, v[50:53] offset:36864
	s_or_b64 exec, exec, s[36:37]
	global_load_dwordx4 v[62:65], v[224:225], off
	v_lshl_add_u64 v[224:225], v[224:225], 0, s[100:101]
	v_pk_fma_f32 v[50:51], v[32:33], v[60:61], v[36:37]
	v_pk_fma_f32 v[52:53], v[30:31], v[58:59], v[34:35]
	v_pk_fma_f32 v[50:51], v[28:29], v[40:41], v[50:51]
	v_pk_fma_f32 v[52:53], v[26:27], v[38:39], v[52:53]
	v_pk_fma_f32 v[50:51], v[24:25], v[48:49], v[50:51]
	v_pk_fma_f32 v[58:59], v[22:23], v[46:47], v[52:53]
	v_pk_fma_f32 v[52:53], v[20:21], v[44:45], v[50:51]
	v_pk_fma_f32 v[50:51], v[18:19], v[42:43], v[58:59]
	v_cvt_pk_bf16_f32 v59, v52, v53
	s_nop 0
	v_cvt_pk_bf16_f32 v58, v50, v51
	ds_write_b64 v176, v[58:59] offset:720
	s_and_saveexec_b64 s[36:37], s[8:9]
	v_add_u32_e32 v58, v137, v153
	ds_write_b128 v58, v[50:53] offset:36864
	s_or_b64 exec, exec, s[36:37]
	global_load_dwordx4 v[58:61], v[224:225], off
	v_lshl_add_u64 v[224:225], v[224:225], 0, s[100:101]
	v_pk_fma_f32 v[40:41], v[32:33], v[40:41], v[36:37]
	v_pk_fma_f32 v[38:39], v[30:31], v[38:39], v[34:35]
	v_pk_fma_f32 v[40:41], v[28:29], v[48:49], v[40:41]
	v_pk_fma_f32 v[38:39], v[26:27], v[46:47], v[38:39]
	v_pk_fma_f32 v[40:41], v[24:25], v[44:45], v[40:41]
	v_pk_fma_f32 v[38:39], v[22:23], v[42:43], v[38:39]
	v_pk_fma_f32 v[40:41], v[20:21], v[56:57], v[40:41]
	v_pk_fma_f32 v[38:39], v[18:19], v[54:55], v[38:39]
	v_cvt_pk_bf16_f32 v43, v40, v41
	s_nop 0
	v_cvt_pk_bf16_f32 v42, v38, v39
	ds_write_b64 v176, v[42:43] offset:864
	s_and_saveexec_b64 s[36:37], s[8:9]
	v_add_u32_e32 v42, v137, v154
	ds_write_b128 v42, v[38:41] offset:36864
	s_or_b64 exec, exec, s[36:37]
	global_load_dwordx4 v[38:41], v[224:225], off
	v_lshl_add_u64 v[224:225], v[224:225], 0, s[100:101]
	v_add_u32_e32 v186, 0x9000, v155
	v_add_u32_e32 v183, 0xd000, v155
	v_add_u32_e32 v184, 0x9000, v161
	v_add_u32_e32 v185, 0xd000, v161
	s_waitcnt lgkmcnt(0)
	s_barrier
; #define LAS __attribute__((address_space(3)))
; __device__ __forceinline__ float fexp(float x) { return __builtin_amdgcn_exp2f(x * 1.44269504089f); }
; __device__ __forceinline__ float fsigmoid(float x) { return __builtin_amdgcn_rcpf(1.0f + fexp(-x)); }
; __device__ __forceinline__ void lru_item(const Args& a, LAS unsigned char* lds, bool sample, int b, int head, int q, int tid, int lane, int wave) {
;     ...
; #pragma unroll
;             for (int tt = 0; tt < 2; ++tt) {
;                 const int tile = 2 * wave + tt;
;                 f32x4 ar = (f32x4){0.f, 0.f, 0.f, 0.f}, ax = ar;
; #pragma unroll
;                 for (int ks = 0; ks < 2; ++ks) {
;                     const bf16x8 af = *(const LAS bf16x8*)(XC + (16 * tile + fr) * XC_PITCH + 64 * ks + 16 * fq);
;                     ar = __builtin_amdgcn_mfma_f32_16x16x32_bf16(af, Bf[0][ks], ar, 0, 0, 0);
;                     ax = __builtin_amdgcn_mfma_f32_16x16x32_bf16(af, Bf[1][ks], ax, 0, 0, 0);
;                 }
; #pragma unroll
;                 for (int r4 = 0; r4 < 4; ++r4) {
;                     const int rr = 16 * tile + 4 * fq + r4;
;                     const float xcv = XCF[rr * 16 + fr];
;                     const float rg_ = fsigmoid(ar[r4] + ba), ig = fsigmoid(ax[r4] + bx_);
;                     const float la = -8.0f * rg_ * spl;
;                     const float av = fexp(la); AA[rr * 16 + fr] = av; BX[rr * 16 + fr] = __builtin_amdgcn_sqrtf(fmaxf(fmaf(-av, av, 1.0f), 0.f)) * (ig * xcv);
;                 }
;             }
;             __syncthreads();
	ds_read_b128 v[118:121], v177
	ds_read_b32 v108, v155 offset:36992
	ds_read_b128 v[126:129], v177 offset:64
	s_waitcnt lgkmcnt(2)
	v_mfma_f32_16x16x32_bf16 v[122:125], v[118:121], v[2:5], 0
	v_mov_b32_e32 v187, v140
	s_waitcnt lgkmcnt(0)
	v_mfma_f32_16x16x32_bf16 v[122:125], v[126:129], v[14:17], v[122:125]
	v_mfma_f32_16x16x32_bf16 v[118:121], v[118:121], v[6:9], 0
	s_nop 6
	v_add_f32_e32 v122, v97, v122
	v_mul_f32_e32 v122, 0xbfb8aa3b, v122
	v_exp_f32_e32 v122, v122
	v_mfma_f32_16x16x32_bf16 v[118:121], v[126:129], v[10:13], v[118:121]
	ds_read2_b32 v[126:127], v186 offset1:16
	v_add_f32_e32 v123, v97, v123
	v_add_f32_e32 v122, 1.0, v122
	v_rcp_f32_e32 v122, v122
	v_mul_f32_e32 v123, 0xbfb8aa3b, v123
	s_nop 2
	v_add_f32_e32 v118, v93, v118
	v_mul_f32_e32 v118, 0xbfb8aa3b, v118
	v_mul_f32_e32 v122, 0xc1000000, v122
	v_mul_f32_e32 v122, v180, v122
	v_mul_f32_e32 v122, 0x3fb8aa3b, v122
	v_exp_f32_e32 v118, v118
	v_exp_f32_e32 v122, v122
	v_exp_f32_e32 v123, v123
	v_add_f32_e32 v119, v93, v119
	v_add_f32_e32 v118, 1.0, v118
	v_fma_f32 v128, -v122, v122, 1.0
	v_rcp_f32_e32 v118, v118
	v_max_f32_e32 v128, 0, v128
	v_sqrt_f32_e32 v128, v128
	v_mul_f32_e32 v119, 0xbfb8aa3b, v119
	s_waitcnt lgkmcnt(0)
	v_mul_f32_e32 v118, v126, v118
	v_exp_f32_e32 v119, v119
	v_mul_f32_e32 v118, v118, v128
	ds_write_b32 v156, v118
	global_load_dwordx4 v[46:49], v[224:225], off
	v_lshl_add_u64 v[224:225], v[224:225], 0, s[100:101]
	v_add_f32_e32 v118, 1.0, v123
	v_rcp_f32_e32 v118, v118
	v_add_f32_e32 v124, v97, v124
	v_add_f32_e32 v119, 1.0, v119
	v_mul_f32_e32 v124, 0xbfb8aa3b, v124
	v_mul_f32_e32 v118, 0xc1000000, v118
	v_mul_f32_e32 v118, v180, v118
	v_mul_f32_e32 v118, 0x3fb8aa3b, v118
	v_exp_f32_e32 v118, v118
	v_rcp_f32_e32 v119, v119
	v_exp_f32_e32 v124, v124
	v_add_f32_e32 v120, v93, v120
	v_fma_f32 v123, -v118, v118, 1.0
	ds_write2_b32 v183, v122, v118 offset1:16
	v_mul_f32_e32 v118, v127, v119
	v_add_f32_e32 v119, 1.0, v124
	v_rcp_f32_e32 v119, v119
	v_max_f32_e32 v123, 0, v123
	v_sqrt_f32_e32 v123, v123
	v_mul_f32_e32 v120, 0xbfb8aa3b, v120
	v_mul_f32_e32 v119, 0xc1000000, v119
	v_mul_f32_e32 v119, v180, v119
	v_mul_f32_e32 v119, 0x3fb8aa3b, v119
	v_exp_f32_e32 v120, v120
	v_exp_f32_e32 v119, v119
	v_mul_f32_e32 v118, v118, v123
	ds_write_b32 v157, v118
	v_add_f32_e32 v118, 1.0, v120
	ds_write_b32 v155, v119 offset:53376
	v_fma_f32 v119, -v119, v119, 1.0
	v_rcp_f32_e32 v118, v118
	v_max_f32_e32 v119, 0, v119
	v_add_f32_e32 v120, v97, v125
	v_sqrt_f32_e32 v119, v119
	v_mul_f32_e32 v120, 0xbfb8aa3b, v120
	v_exp_f32_e32 v120, v120
	v_mul_f32_e32 v108, v118, v108
	v_mul_f32_e32 v108, v108, v119
	ds_write_b32 v158, v108
	v_add_f32_e32 v108, 1.0, v120
	global_load_dwordx4 v[42:45], v[224:225], off
	v_lshl_add_u64 v[224:225], v[224:225], 0, s[100:101]
	v_rcp_f32_e32 v108, v108
	v_add_f32_e32 v118, v93, v121
	v_mul_f32_e32 v118, 0xbfb8aa3b, v118
	v_exp_f32_e32 v118, v118
	v_mul_f32_e32 v108, 0xc1000000, v108
	v_mul_f32_e32 v108, v180, v108
	v_mul_f32_e32 v108, 0x3fb8aa3b, v108
	v_exp_f32_e32 v108, v108
	ds_read_b32 v119, v159 offset:36864
	v_add_f32_e32 v118, 1.0, v118
	v_rcp_f32_e32 v118, v118
	v_fma_f32 v120, -v108, v108, 1.0
	v_max_f32_e32 v120, 0, v120
	v_sqrt_f32_e32 v120, v120
	ds_write_b32 v159, v108 offset:53248
	s_waitcnt lgkmcnt(1)
	v_mul_f32_e32 v108, v118, v119
	v_mul_f32_e32 v108, v108, v120
	ds_write_b32 v160, v108
	ds_read_b128 v[118:121], v178
	ds_read_b32 v108, v161 offset:36992
	ds_read_b128 v[126:129], v178 offset:64
	s_waitcnt lgkmcnt(2)
	v_mfma_f32_16x16x32_bf16 v[122:125], v[118:121], v[2:5], 0
	s_waitcnt lgkmcnt(0)
	v_mfma_f32_16x16x32_bf16 v[122:125], v[126:129], v[14:17], v[122:125]
	v_mfma_f32_16x16x32_bf16 v[118:121], v[118:121], v[6:9], 0
	s_nop 6
	v_add_f32_e32 v122, v97, v122
	v_mul_f32_e32 v122, 0xbfb8aa3b, v122
	v_exp_f32_e32 v122, v122
	v_mfma_f32_16x16x32_bf16 v[118:121], v[126:129], v[10:13], v[118:121]
	ds_read2_b32 v[126:127], v184 offset1:16
	v_add_f32_e32 v123, v97, v123
	v_add_f32_e32 v122, 1.0, v122
	v_rcp_f32_e32 v122, v122
	v_mul_f32_e32 v123, 0xbfb8aa3b, v123
	s_nop 2
	v_add_f32_e32 v118, v93, v118
	global_load_dwordx4 v[54:57], v[224:225], off
	v_mul_f32_e32 v118, 0xbfb8aa3b, v118
	v_mul_f32_e32 v122, 0xc1000000, v122
	v_mul_f32_e32 v122, v180, v122
	v_mul_f32_e32 v122, 0x3fb8aa3b, v122
	v_exp_f32_e32 v118, v118
	v_exp_f32_e32 v122, v122
	v_exp_f32_e32 v123, v123
	v_add_f32_e32 v119, v93, v119
	v_add_f32_e32 v118, 1.0, v118
	v_fma_f32 v128, -v122, v122, 1.0
	v_rcp_f32_e32 v118, v118
	v_max_f32_e32 v128, 0, v128
	v_sqrt_f32_e32 v128, v128
	v_mul_f32_e32 v119, 0xbfb8aa3b, v119
	s_waitcnt lgkmcnt(0)
	v_mul_f32_e32 v118, v126, v118
	v_exp_f32_e32 v119, v119
	v_mul_f32_e32 v118, v118, v128
	ds_write_b32 v164, v118
	v_add_f32_e32 v118, 1.0, v123
	v_rcp_f32_e32 v118, v118
	v_add_f32_e32 v124, v97, v124
	v_add_f32_e32 v119, 1.0, v119
	v_mul_f32_e32 v124, 0xbfb8aa3b, v124
	v_mul_f32_e32 v118, 0xc1000000, v118
	v_mul_f32_e32 v118, v180, v118
	v_mul_f32_e32 v118, 0x3fb8aa3b, v118
	v_exp_f32_e32 v118, v118
	v_rcp_f32_e32 v119, v119
	v_exp_f32_e32 v124, v124
	v_add_f32_e32 v120, v93, v120
	v_fma_f32 v123, -v118, v118, 1.0
	ds_write2_b32 v185, v122, v118 offset1:16
	v_mul_f32_e32 v118, v127, v119
	v_add_f32_e32 v119, 1.0, v124
	v_rcp_f32_e32 v119, v119
	v_max_f32_e32 v123, 0, v123
	v_sqrt_f32_e32 v123, v123
	v_mul_f32_e32 v120, 0xbfb8aa3b, v120
	v_mul_f32_e32 v119, 0xc1000000, v119
	v_add_u32_e32 v226, s30, v181
	v_ashrrev_i32_e32 v227, 31, v226
	v_lshlrev_b64 v[226:227], 11, v[226:227]
	v_lshl_add_u64 v[226:227], v[112:113], 0, v[226:227]
	global_load_dwordx4 v[50:53], v[226:227], off
	v_mul_f32_e32 v119, v180, v119
	v_mul_f32_e32 v119, 0x3fb8aa3b, v119
	v_exp_f32_e32 v120, v120
	v_exp_f32_e32 v119, v119
	v_mul_f32_e32 v118, v118, v123
	ds_write_b32 v165, v118
	v_add_f32_e32 v118, 1.0, v120
	ds_write_b32 v161, v119 offset:53376
	v_fma_f32 v119, -v119, v119, 1.0
	v_rcp_f32_e32 v118, v118
	v_max_f32_e32 v119, 0, v119
	v_add_f32_e32 v120, v97, v125
	v_sqrt_f32_e32 v119, v119
	v_mul_f32_e32 v120, 0xbfb8aa3b, v120
	v_exp_f32_e32 v120, v120
	v_mul_f32_e32 v108, v118, v108
	v_mul_f32_e32 v108, v108, v119
	ds_write_b32 v166, v108
	v_add_f32_e32 v108, 1.0, v120
	v_rcp_f32_e32 v108, v108
	v_add_f32_e32 v118, v93, v121
	v_mul_f32_e32 v118, 0xbfb8aa3b, v118
	v_exp_f32_e32 v118, v118
	v_mul_f32_e32 v108, 0xc1000000, v108
	v_mul_f32_e32 v108, v180, v108
	v_mul_f32_e32 v108, 0x3fb8aa3b, v108
	v_exp_f32_e32 v108, v108
	ds_read_b32 v119, v167 offset:36864
	v_add_f32_e32 v118, 1.0, v118
	v_rcp_f32_e32 v118, v118
	v_fma_f32 v120, -v108, v108, 1.0
	v_max_f32_e32 v120, 0, v120
	v_sqrt_f32_e32 v120, v120
	ds_write_b32 v167, v108 offset:53248
	s_waitcnt lgkmcnt(1)
	v_mul_f32_e32 v108, v118, v119
	v_mul_f32_e32 v108, v108, v120
	ds_write_b32 v168, v108
	v_mov_b32_e32 v108, v139
	s_waitcnt lgkmcnt(0)
	s_barrier
; #define LAS __attribute__((address_space(3)))
; __device__ __forceinline__ void lru_item(const Args& a, LAS unsigned char* lds, bool sample, int b, int head, int q, int tid, int lane, int wave) {
;     ...
;             const int sn = tid & 15, sg = tid >> 4;
;             float av[8], bv[8];
;             const LAS float* ap = AA + (8 * sg) * 16 + sn; LAS float* bp = BX + (8 * sg) * 16 + sn;
;             asm volatile("" : "+v"(ap), "+v"(bp));
;             { float P = 1.f, h = 0.f;
; #pragma unroll
;               for (int i = 0; i < 8; ++i) { av[i] = ap[i * 16]; bv[i] = bp[i * 16]; }
; #pragma unroll
;               for (int i = 0; i < 8; ++i) { h = av[i] * h + bv[i]; P *= av[i]; }
;               SEGP[tid] = P; SEGH[tid] = h; }
;             __syncthreads();
;             if (wave == 0 && lane < 16) {
;                 const LAS float* pp = SEGP + lane; const LAS float* hp = SEGH + lane; LAS float* cp = CAR + lane;
;                 asm volatile("" : "+v"(pp), "+v"(hp), "+v"(cp));
;                 float run = hcar;
; #pragma unroll
;                 for (int h2 = 0; h2 < 2; ++h2) {
;                     float sp_[16], sh_[16];
; #pragma unroll
;                     for (int s2 = 0; s2 < 16; ++s2) { sp_[s2] = pp[(16 * h2 + s2) * 16]; sh_[s2] = hp[(16 * h2 + s2) * 16]; }
; #pragma unroll
;                     for (int s2 = 0; s2 < 16; ++s2) { cp[(16 * h2 + s2) * 16] = run; run = sp_[s2] * run + sh_[s2]; }
;                 }
;                 hcar = run;
;             }
	ds_read2_b32 v[132:133], v108 offset1:16
	ds_read2_b32 v[130:131], v187 offset1:16
	ds_read2_b32 v[128:129], v108 offset0:32 offset1:48
	ds_read2_b32 v[126:127], v187 offset0:32 offset1:48
	ds_read2_b32 v[124:125], v108 offset0:64 offset1:80
	ds_read2_b32 v[122:123], v187 offset0:64 offset1:80
	ds_read2_b32 v[118:119], v108 offset0:96 offset1:112
	ds_read2_b32 v[120:121], v187 offset0:96 offset1:112
	s_waitcnt lgkmcnt(6)
	v_fma_f32 v108, 0, v132, v130
	v_mul_f32_e32 v188, v132, v133
	v_fma_f32 v108, v108, v133, v131
	s_waitcnt lgkmcnt(5)
	v_mul_f32_e32 v188, v188, v128
	s_waitcnt lgkmcnt(4)
	v_fma_f32 v108, v108, v128, v126
	v_mul_f32_e32 v188, v188, v129
	v_fma_f32 v108, v108, v129, v127
	s_waitcnt lgkmcnt(3)
	v_mul_f32_e32 v188, v188, v124
	s_waitcnt lgkmcnt(2)
	v_fma_f32 v108, v108, v124, v122
	v_mul_f32_e32 v188, v188, v125
	v_fma_f32 v108, v108, v125, v123
	s_waitcnt lgkmcnt(1)
	v_mul_f32_e32 v188, v188, v118
	s_waitcnt lgkmcnt(0)
	v_fma_f32 v108, v108, v118, v120
	v_mul_f32_e32 v188, v188, v119
	v_fma_f32 v108, v108, v119, v121
	ds_write_b32 v141, v188
	ds_write_b32 v142, v108
	s_waitcnt lgkmcnt(0)
	s_barrier
	s_and_saveexec_b64 s[36:37], s[18:19]
	s_cbranch_execz .LBB0_690
	v_mov_b32_e32 v108, v144
	v_mov_b32_e32 v211, v143
	v_mov_b32_e32 v222, v145
	ds_read2_b32 v[188:189], v211 offset1:16
	ds_read2_b32 v[190:191], v108 offset1:16
	ds_read2_b32 v[192:193], v211 offset0:32 offset1:48
	ds_read2_b32 v[194:195], v108 offset0:32 offset1:48
	ds_read2_b32 v[196:197], v211 offset0:64 offset1:80
	ds_read2_b32 v[198:199], v108 offset0:64 offset1:80
	ds_read2_b32 v[200:201], v211 offset0:96 offset1:112
	ds_read2_b32 v[202:203], v108 offset0:96 offset1:112
	ds_read2_b32 v[204:205], v211 offset0:128 offset1:144
	ds_read2_b32 v[206:207], v108 offset0:128 offset1:144
	ds_read2_b32 v[208:209], v211 offset0:160 offset1:176
	ds_read2_b32 v[212:213], v108 offset0:160 offset1:176
	ds_read2_b32 v[214:215], v211 offset0:192 offset1:208
	ds_read2_b32 v[216:217], v108 offset0:192 offset1:208
	ds_read2_b32 v[218:219], v211 offset0:224 offset1:240
	ds_read2_b32 v[220:221], v108 offset0:224 offset1:240
	s_waitcnt lgkmcnt(14)
	v_fma_f32 v188, v109, v188, v190
	v_fmac_f32_e32 v191, v188, v189
	ds_write2_b32 v222, v109, v188 offset1:16
	s_waitcnt lgkmcnt(13)
	v_fma_f32 v109, v191, v192, v194
	v_fmac_f32_e32 v195, v109, v193
	ds_write2_b32 v222, v191, v109 offset0:32 offset1:48
	s_waitcnt lgkmcnt(12)
	v_fma_f32 v109, v195, v196, v198
	v_fmac_f32_e32 v199, v109, v197
	ds_write2_b32 v222, v195, v109 offset0:64 offset1:80
	s_waitcnt lgkmcnt(11)
	v_fma_f32 v109, v199, v200, v202
	v_fmac_f32_e32 v203, v109, v201
	ds_write2_b32 v222, v199, v109 offset0:96 offset1:112
	s_waitcnt lgkmcnt(10)
	v_fma_f32 v109, v203, v204, v206
	v_fmac_f32_e32 v207, v109, v205
	ds_write2_b32 v222, v203, v109 offset0:128 offset1:144
	s_waitcnt lgkmcnt(9)
	v_fma_f32 v109, v207, v208, v212
	v_fmac_f32_e32 v213, v109, v209
	ds_write2_b32 v222, v207, v109 offset0:160 offset1:176
	s_waitcnt lgkmcnt(8)
	v_fma_f32 v109, v213, v214, v216
	v_fmac_f32_e32 v217, v109, v215
	ds_write2_b32 v222, v213, v109 offset0:192 offset1:208
	s_waitcnt lgkmcnt(7)
	v_fma_f32 v109, v217, v218, v220
	ds_write2_b32 v222, v217, v109 offset0:224 offset1:240
	v_fmac_f32_e32 v221, v109, v219
	v_add_u32_e32 v109, 0x400, v211
	ds_read2_b32 v[188:189], v109 offset1:16
	v_add_u32_e32 v108, 0x400, v108
	ds_read2_b32 v[190:191], v108 offset1:16
	ds_read2_b32 v[192:193], v109 offset0:32 offset1:48
	ds_read2_b32 v[194:195], v108 offset0:32 offset1:48
	ds_read2_b32 v[196:197], v109 offset0:64 offset1:80
	ds_read2_b32 v[198:199], v108 offset0:64 offset1:80
	ds_read2_b32 v[200:201], v109 offset0:96 offset1:112
	ds_read2_b32 v[202:203], v108 offset0:96 offset1:112
	ds_read2_b32 v[204:205], v109 offset0:128 offset1:144
	ds_read2_b32 v[206:207], v108 offset0:128 offset1:144
	ds_read2_b32 v[208:209], v109 offset0:160 offset1:176
	ds_read2_b32 v[212:213], v108 offset0:160 offset1:176
	ds_read2_b32 v[214:215], v109 offset0:192 offset1:208
	ds_read2_b32 v[216:217], v108 offset0:192 offset1:208
	ds_read2_b32 v[218:219], v109 offset0:224 offset1:240
	ds_read2_b32 v[108:109], v108 offset0:224 offset1:240
	s_waitcnt lgkmcnt(14)
	v_fma_f32 v188, v221, v188, v190
	v_add_u32_e32 v190, 0x400, v222
	v_fmac_f32_e32 v191, v188, v189
	ds_write2_b32 v190, v221, v188 offset1:16
	s_waitcnt lgkmcnt(13)
	v_fma_f32 v188, v191, v192, v194
	v_fmac_f32_e32 v195, v188, v193
	ds_write2_b32 v190, v191, v188 offset0:32 offset1:48
	s_waitcnt lgkmcnt(12)
	v_fma_f32 v188, v195, v196, v198
	v_fmac_f32_e32 v199, v188, v197
	ds_write2_b32 v190, v195, v188 offset0:64 offset1:80
	s_waitcnt lgkmcnt(11)
	v_fma_f32 v188, v199, v200, v202
	v_fmac_f32_e32 v203, v188, v201
	ds_write2_b32 v190, v199, v188 offset0:96 offset1:112
	s_waitcnt lgkmcnt(10)
	v_fma_f32 v188, v203, v204, v206
	v_fmac_f32_e32 v207, v188, v205
	ds_write2_b32 v190, v203, v188 offset0:128 offset1:144
	s_waitcnt lgkmcnt(9)
	v_fma_f32 v188, v207, v208, v212
	v_fmac_f32_e32 v213, v188, v209
	ds_write2_b32 v190, v207, v188 offset0:160 offset1:176
	s_waitcnt lgkmcnt(8)
	v_fma_f32 v188, v213, v214, v216
	v_fmac_f32_e32 v217, v188, v215
	s_waitcnt lgkmcnt(6)
	v_fma_f32 v108, v217, v218, v108
	v_fmac_f32_e32 v109, v108, v219
	ds_write2_b32 v190, v213, v188 offset0:192 offset1:208
	ds_write2_b32 v190, v217, v108 offset0:224 offset1:240
